# gla_scan fast loop: 14 v_add_co/s_nop/v_addc literal address triples fused into v_lshl_add_u64 with SGPR-pair constants; fast loop also takes c=58
# baseline (speedup 1.0000x reference)
; DI void phase_gla_scan(const Params& p, LAS unsigned char* lds) {
;     ...
; #pragma unroll
;         for (int i = 0; i < 16; ++i) st[i] = 0.f;
;         u32x4 rkA[4], rvA, rkB[4], rvB; float rtA = 0.f, rtB = 0.f; bf16x8 qa[8], qn[8];
;         rvA = (u32x4){0u, 0u, 0u, 0u}; rvB = rvA;
;         unsigned offk[4];
; #pragma unroll
;         for (int i = 0; i < 4; ++i) { const int idx = tid + i * 512, row = idx >> 5, cc = idx & 31; offk[i] = (unsigned)((row * 6400 + 1024 + h * 256 + cc * 8) * 2); }
;         const unsigned offv = (unsigned)(((tid >> 2) * 6400 + 2048 + h * 512 + vs * 32 + (tid & 3) * 8) * 2);
;         const unsigned offq = (unsigned)(((16 * mt + i16) * 6400 + h * 256 + 8 * quad) * 2);
;         auto gload = [&](int c, u32x4 (&rk)[4], u32x4& rv, float& rt) {
;             const char* cb = (const char*)(big + (tok0 + (size_t)c * 64) * 6400);
; #pragma unroll
;             for (int i = 0; i < 4; ++i) rk[i] = *(const u32x4*)(cb + offk[i]);
;             if (tid < 256) { rv = *(const u32x4*)(cb + offv); rt = total[(size_t)(b * 64 + c) * 1024 + h * 256 + tid]; }
;         };
;         auto lstore = [&](int buf, const u32x4 (&rk)[4], const u32x4& rv, const float& rt) {
;             LAS unsigned char* sb = lds + buf * SET;
; #pragma unroll
;             for (int i = 0; i < 4; ++i) { const int idx = tid + i * 512, row = idx >> 5, cc = idx & 31; *(LAS u32x4*)(sb + row * KR + cc * 16) = rk[i]; }
;             if (tid < 256) { const int row = tid >> 2, cc = tid & 3; *(LAS u32x4*)(sb + 64 * KR + row * VR + cc * 16) = rv; ((LAS float*)(sb + 64 * KR + 64 * VR))[tid] = __expf(rt); }
;         };
;         auto qload = [&](int c, bf16x8 (&q)[8]) {
;             const char* cb = (const char*)(big + (tok0 + (size_t)c * 64) * 6400) + offq;
; #pragma unroll
;             for (int ks = 0; ks < 8; ++ks) q[ks] = *(const bf16x8*)(cb + 64 * ks);
;         };
;         auto step = [&](int c, const bf16x8 (&qc)[8]) {
;             LAS unsigned char* sb = lds + (c & 1) * SET; LAS unsigned char* stb = lds + ST_OFF + (c & 1) * STB;
; #pragma unroll
;             for (int g = 0; g < 4; ++g) { const f32x4 e = *(LAS const f32x4*)(sb + 64 * KR + 64 * VR + (32 * w + 8 * g + 4 * hh) * 4);
;                 st[4 * g] *= e[0]; st[4 * g + 1] *= e[1]; st[4 * g + 2] *= e[2]; st[4 * g + 3] *= e[3]; }
; #pragma unroll
;             for (int sx = 0; sx < 4; ++sx) {
.LBB0_584:
	s_or_b64 exec, exec, s[42:43]
	v_add_u32_e32 v4, s49, v160
	global_load_dwordx4 v[56:59], v4, s[36:37]
	global_load_dwordx4 v[60:63], v4, s[36:37] offset:64
	global_load_dwordx4 v[64:67], v4, s[36:37] offset:128
	global_load_dwordx4 v[68:71], v4, s[36:37] offset:192
	global_load_dwordx4 v[72:75], v4, s[36:37] offset:256
	global_load_dwordx4 v[80:83], v4, s[36:37] offset:320
	global_load_dwordx4 v[88:91], v4, s[36:37] offset:384
	global_load_dwordx4 v[96:99], v4, s[36:37] offset:448
	global_load_dwordx4 v[76:79], v4, s[38:39]
	global_load_dwordx4 v[84:87], v4, s[38:39] offset:64
	global_load_dwordx4 v[92:95], v4, s[38:39] offset:128
	global_load_dwordx4 v[100:103], v4, s[38:39] offset:192
	global_load_dwordx4 v[104:107], v4, s[38:39] offset:256
	global_load_dwordx4 v[108:111], v4, s[38:39] offset:320
	global_load_dwordx4 v[112:115], v4, s[38:39] offset:384
	global_load_dwordx4 v[116:119], v4, s[38:39] offset:448
	s_ashr_i32 s31, s30, 31
	s_lshl_b64 s[36:37], s[30:31], 12
	v_lshlrev_b32_e32 v2, 2, v2
	v_mov_b32_e32 v3, v131
	s_add_i32 s50, s50, s49
	v_mov_b32_e32 v5, v131
	v_lshl_add_u64 v[132:133], v[124:125], 0, v[2:3]
	v_lshl_add_u64 v[134:135], s[34:35], 0, v[130:131]
	v_add_lshl_u32 v130, s50, v129, 1
	s_lshl_b32 s24, s48, 6
	v_lshl_add_u64 v[2:3], v[122:123], 0, s[36:37]
	v_lshl_add_u64 v[136:137], s[34:35], 0, v[136:137]
	v_lshl_add_u64 v[138:139], s[34:35], 0, v[138:139]
	v_lshl_add_u64 v[140:141], s[34:35], 0, v[140:141]
	v_lshl_add_u64 v[142:143], s[34:35], 0, v[130:131]
	v_lshl_add_u64 v[144:145], s[34:35], 0, v[4:5]
	s_and_b32 s34, s24, 0xc00
	s_and_b32 s24, s24, 0x3c0
	v_lshlrev_b64 v[148:149], 12, v[2:3]
	s_lshl_b64 s[30:31], s[30:31], 24
	s_or_b32 s35, s24, s34
	v_or_b32_e32 v1, v128, v148
	s_or_b32 s30, s30, s35
	v_or_b32_e32 v1, s34, v1
	v_lshl_add_u64 v[146:147], s[30:31], 0, v[126:127]
	v_or_b32_e32 v148, s24, v1
	s_mov_b32 s24, 0
	v_mov_b32_e32 v1, v0
	v_mov_b32_e32 v2, v0
	v_mov_b32_e32 v3, v0
	v_mov_b32_e32 v4, v0
	v_mov_b32_e32 v5, v0
	v_mov_b32_e32 v6, v0
	v_mov_b32_e32 v7, v0
	v_mov_b32_e32 v8, v0
	v_mov_b32_e32 v9, v0
	v_mov_b32_e32 v10, v0
	v_mov_b32_e32 v11, v0
	v_mov_b32_e32 v12, v0
	v_mov_b32_e32 v13, v0
	v_mov_b32_e32 v14, v0
	v_mov_b32_e32 v15, v0
	s_mov_b32 s92, 0xc158000
	s_mov_b32 s93, 0
	s_mov_b32 s94, 0xc220000
	s_mov_b32 s95, 0
	s_mov_b32 s96, 0xc090000
	s_mov_b32 s97, 0
	s_mov_b32 s98, 0x7f02000
	s_mov_b32 s99, 0
	s_mov_b32 s100, 0x7f03000
	s_mov_b32 s101, 0
	s_waitcnt vmcnt(0) lgkmcnt(0)
	s_barrier
	s_branch .Lgs_586

; DI void phase_gla_scan(const Params& p, LAS unsigned char* lds) {
;     ...
;         auto gload = [&](int c, u32x4 (&rk)[4], u32x4& rv, float& rt) {
;             const char* cb = (const char*)(big + (tok0 + (size_t)c * 64) * 6400);
; #pragma unroll
;             for (int i = 0; i < 4; ++i) rk[i] = *(const u32x4*)(cb + offk[i]);
;             if (tid < 256) { rv = *(const u32x4*)(cb + offv); rt = total[(size_t)(b * 64 + c) * 1024 + h * 256 + tid]; }
;         };
.Lgs_588:
	s_or_b64 exec, exec, s[30:31]
	s_cmp_lt_u32 s24, 61
	s_cselect_b64 s[30:31], -1, 0
	s_cmp_gt_u32 s24, 60
	v_lshl_add_u64 v[156:157], s[12:13], 0, v[134:135]
	v_lshl_add_u64 v[154:155], s[12:13], 0, v[136:137]
	v_lshl_add_u64 v[152:153], s[12:13], 0, v[138:139]
	v_lshl_add_u64 v[150:151], s[12:13], 0, v[140:141]
	s_cbranch_scc1 .Lgs_592
	v_lshl_add_u64 v[20:21], v[156:157], 0, s[92:93]
	v_lshl_add_u64 v[24:25], v[154:155], 0, s[92:93]
	v_lshl_add_u64 v[28:29], v[152:153], 0, s[92:93]
	global_load_dwordx4 v[20:23], v[20:21], off
	s_nop 0
	global_load_dwordx4 v[24:27], v[24:25], off
	v_lshl_add_u64 v[32:33], v[150:151], 0, s[92:93]
	global_load_dwordx4 v[28:31], v[28:29], off
	s_nop 0
	global_load_dwordx4 v[32:35], v[32:33], off
	s_and_saveexec_b64 s[34:35], s[8:9]
	s_cbranch_execz .Lgs_591
	v_add3_u32 v16, v195, s24, 3
	v_ashrrev_i32_e32 v17, 31, v16
	v_lshlrev_b64 v[16:17], 12, v[16:17]
	v_lshl_add_u64 v[158:159], v[132:133], 0, v[16:17]
	v_lshl_add_u64 v[16:17], s[12:13], 0, v[142:143]
	v_lshl_add_u64 v[16:17], v[16:17], 0, s[92:93]
	global_load_dwordx4 v[16:19], v[16:17], off
	s_nop 0
	global_load_dword v194, v[158:159], off

; DI void phase_gla_scan(const Params& p, LAS unsigned char* lds) {
;     ...
;         auto lstore = [&](int buf, const u32x4 (&rk)[4], const u32x4& rv, const float& rt) {
;             LAS unsigned char* sb = lds + buf * SET;
; #pragma unroll
;             for (int i = 0; i < 4; ++i) { const int idx = tid + i * 512, row = idx >> 5, cc = idx & 31; *(LAS u32x4*)(sb + row * KR + cc * 16) = rk[i]; }
;             if (tid < 256) { const int row = tid >> 2, cc = tid & 3; *(LAS u32x4*)(sb + 64 * KR + row * VR + cc * 16) = rv; ((LAS float*)(sb + 64 * KR + 64 * VR))[tid] = __expf(rt); }
;         };
;         auto qload = [&](int c, bf16x8 (&q)[8]) {
;             const char* cb = (const char*)(big + (tok0 + (size_t)c * 64) * 6400) + offq;
; #pragma unroll
;             for (int ks = 0; ks < 8; ++ks) q[ks] = *(const bf16x8*)(cb + 64 * ks);
;         };
;         auto step = [&](int c, const bf16x8 (&qc)[8]) {
;             LAS unsigned char* sb = lds + (c & 1) * SET; LAS unsigned char* stb = lds + ST_OFF + (c & 1) * STB;
; #pragma unroll
;             for (int g = 0; g < 4; ++g) { const f32x4 e = *(LAS const f32x4*)(sb + 64 * KR + 64 * VR + (32 * w + 8 * g + 4 * hh) * 4);
;                 st[4 * g] *= e[0]; st[4 * g + 1] *= e[1]; st[4 * g + 2] *= e[2]; st[4 * g + 3] *= e[3]; }
; #pragma unroll
;             for (int sx = 0; sx < 4; ++sx) {
;                 LAS unsigned char* ka = sb + (16 * sx + 8 * hh + tq) * KR + (32 * w + 16 * blk + 4 * tp) * 2;
;                 LAS unsigned char* va = sb + 64 * KR + (16 * sx + 8 * hh + tq) * VR + (16 * blk + 4 * tp) * 2;
;                 const bf16x8 af = cat4(trread(ka), trread(ka + 4 * KR)), bfv = cat4(trread(va), trread(va + 4 * VR));
;                 st = mfma32(af, bfv, st);
;             }
; #pragma unroll
;             for (int g = 0; g < 4; ++g) { u32x2 wv; wv.x = pk2(st[4 * g], st[4 * g + 1]); wv.y = pk2(st[4 * g + 2], st[4 * g + 3]);
;                 *(LAS u32x2*)(stb + l32 * SR + (32 * w + 8 * g + 4 * hh) * 2) = wv; }
;             asm volatile("s_waitcnt lgkmcnt(0)" ::: "memory");
;             __builtin_amdgcn_s_barrier();
;             asm volatile("" ::: "memory");
;             f32x4 acc = {0.f, 0.f, 0.f, 0.f};
; #pragma unroll
;             for (int ks = 0; ks < 8; ++ks) {
;                 const bf16x8 bb = *(LAS const bf16x8*)(stb + (16 * nt + i16) * SR + (32 * ks + 8 * quad) * 2);
.Lgs_592:
	ds_read_b128 v[198:201], v169 offset:41056
	ds_read_b128 v[202:205], v169 offset:41024
	ds_read_b128 v[206:209], v169 offset:40960
	ds_read_b128 v[210:213], v169 offset:40992
	ds_read_b64_tr_b16 v[214:215], v190
	ds_read_b64_tr_b16 v[216:217], v190 offset:2304
	ds_read_b64_tr_b16 v[218:219], v170 offset:36864
	ds_read_b64_tr_b16 v[220:221], v170 offset:37120
	s_waitcnt lgkmcnt(7)
	v_pk_mul_f32 v[12:13], v[12:13], v[198:199]
	s_waitcnt lgkmcnt(6)
	v_pk_mul_f32 v[8:9], v[8:9], v[202:203]
	s_waitcnt lgkmcnt(4)
	v_pk_mul_f32 v[4:5], v[4:5], v[210:211]
	v_pk_mul_f32 v[0:1], v[0:1], v[206:207]
	v_pk_mul_f32 v[14:15], v[14:15], v[200:201]
	v_pk_mul_f32 v[10:11], v[10:11], v[204:205]
	v_pk_mul_f32 v[6:7], v[6:7], v[212:213]
	v_pk_mul_f32 v[2:3], v[2:3], v[208:209]
	ds_read_b64_tr_b16 v[198:199], v191
	ds_read_b64_tr_b16 v[200:201], v191 offset:2304
	ds_read_b64_tr_b16 v[202:203], v171 offset:36864
	ds_read_b64_tr_b16 v[204:205], v171 offset:37120
	s_waitcnt lgkmcnt(4)
	v_mfma_f32_32x32x16_bf16 v[0:15], v[214:217], v[218:221], v[0:15]
	s_cmp_gt_u32 s24, 61
	s_cselect_b64 s[34:35], -1, 0
	s_waitcnt lgkmcnt(0)
	v_mfma_f32_32x32x16_bf16 v[0:15], v[198:201], v[202:205], v[0:15]
	ds_read_b64_tr_b16 v[198:199], v192
	ds_read_b64_tr_b16 v[200:201], v192 offset:2304
	ds_read_b64_tr_b16 v[202:203], v172 offset:36864
	ds_read_b64_tr_b16 v[204:205], v172 offset:37120
	s_waitcnt lgkmcnt(0)
	v_mfma_f32_32x32x16_bf16 v[0:15], v[198:201], v[202:205], v[0:15]
	ds_read_b64_tr_b16 v[198:199], v193
	ds_read_b64_tr_b16 v[200:201], v193 offset:2304
	ds_read_b64_tr_b16 v[202:203], v173 offset:36864
	ds_read_b64_tr_b16 v[204:205], v173 offset:37120
	s_waitcnt lgkmcnt(0)
	v_mfma_f32_32x32x16_bf16 v[0:15], v[198:201], v[202:205], v[0:15]
	s_nop 11
	v_cvt_pk_bf16_f32 v158, v0, v1
	v_cvt_pk_bf16_f32 v159, v2, v3
	v_cvt_pk_bf16_f32 v198, v4, v5
	v_cvt_pk_bf16_f32 v199, v6, v7
	v_cvt_pk_bf16_f32 v200, v8, v9
	v_cvt_pk_bf16_f32 v201, v10, v11
	v_cvt_pk_bf16_f32 v202, v12, v13
	v_cvt_pk_bf16_f32 v203, v14, v15
	ds_write2_b64 v174, v[158:159], v[198:199] offset1:2
	ds_write2_b64 v174, v[200:201], v[202:203] offset0:4 offset1:6
	s_waitcnt lgkmcnt(0)
	s_barrier
	ds_read_b128 v[198:201], v175
	ds_read_b128 v[202:205], v175 offset:64
	s_waitcnt vmcnt(27) lgkmcnt(1)
	v_mfma_f32_16x16x32_bf16 v[198:201], v[56:59], v[198:201], 0
	v_lshl_add_u64 v[158:159], s[12:13], 0, v[148:149]
	v_add_co_u32_e32 v210, vcc, s45, v158
	s_waitcnt vmcnt(26) lgkmcnt(0)
	v_mfma_f32_16x16x32_bf16 v[198:201], v[60:63], v[202:205], v[198:201]
	ds_read_b128 v[202:205], v175 offset:128
	ds_read_b128 v[206:209], v175 offset:192
	v_addc_co_u32_e32 v211, vcc, 0, v159, vcc
	s_waitcnt vmcnt(25) lgkmcnt(1)
	v_mfma_f32_16x16x32_bf16 v[198:201], v[64:67], v[202:205], v[198:201]
	ds_read_b128 v[202:205], v175 offset:256
	v_lshl_add_u64 v[212:213], v[158:159], 0, s[98:99]
	s_waitcnt vmcnt(24) lgkmcnt(1)
	v_mfma_f32_16x16x32_bf16 v[198:201], v[68:71], v[206:209], v[198:201]
	ds_read_b128 v[206:209], v175 offset:320
	s_waitcnt vmcnt(23) lgkmcnt(1)
	v_mfma_f32_16x16x32_bf16 v[198:201], v[72:75], v[202:205], v[198:201]
	ds_read_b128 v[202:205], v175 offset:384
	v_lshl_add_u64 v[158:159], v[158:159], 0, s[100:101]
	s_waitcnt vmcnt(22) lgkmcnt(1)
	v_mfma_f32_16x16x32_bf16 v[198:201], v[80:83], v[206:209], v[198:201]
	ds_read_b128 v[206:209], v175 offset:448
	s_waitcnt vmcnt(21) lgkmcnt(1)
	v_mfma_f32_16x16x32_bf16 v[198:201], v[88:91], v[202:205], v[198:201]
	s_and_b64 vcc, exec, s[34:35]
	s_waitcnt vmcnt(20) lgkmcnt(0)
	v_mfma_f32_16x16x32_bf16 v[198:201], v[96:99], v[206:209], v[198:201]
	s_nop 7
	v_mul_f32_e32 v130, 0x3d800000, v198
	v_mul_f32_e32 v197, 0x3d800000, v199
	v_mul_f32_e32 v199, 0x3d800000, v201
	v_mul_f32_e32 v198, 0x3d800000, v200
	v_cvt_pk_bf16_f32 v130, v130, s0
	v_cvt_pk_bf16_f32 v199, v199, s0
	v_cvt_pk_bf16_f32 v197, v197, s0
	v_cvt_pk_bf16_f32 v198, v198, s0
	global_store_short v[210:211], v130, off offset:-4096
	global_store_short v[210:211], v197, off
	global_store_short v[212:213], v198, off
	global_store_short v[158:159], v199, off
	v_lshl_add_u64 v[158:159], s[12:13], 0, v[144:145]
	s_cbranch_vccnz .Lgs_596
	v_lshl_add_u64 v[96:97], v[158:159], 0, s[96:97]
	global_load_dwordx4 v[56:59], v[96:97], off
	global_load_dwordx4 v[60:63], v[96:97], off offset:64
	global_load_dwordx4 v[64:67], v[96:97], off offset:128
	global_load_dwordx4 v[68:71], v[96:97], off offset:192
	global_load_dwordx4 v[72:75], v[96:97], off offset:256
	global_load_dwordx4 v[80:83], v[96:97], off offset:320
	global_load_dwordx4 v[88:91], v[96:97], off offset:384
	s_nop 0
	global_load_dwordx4 v[96:99], v[96:97], off offset:448
	s_waitcnt vmcnt(28)
	ds_write_b128 v185, v[36:39]
	ds_write_b128 v186, v[40:43]
	ds_write_b128 v187, v[44:47]
	ds_write_b128 v188, v[48:51]
	s_and_saveexec_b64 s[36:37], s[8:9]
	s_cbranch_execz .Lgs_595
	v_mul_f32_e32 v130, 0x3fb8aa3b, v196
	v_exp_f32_e32 v130, v130
	ds_write_b128 v189, v[52:55] offset:36864
	ds_write_b32 v161, v130 offset:40960

; DI void phase_gla_scan(const Params& p, LAS unsigned char* lds) {
;     ...
;         auto gload = [&](int c, u32x4 (&rk)[4], u32x4& rv, float& rt) {
;             const char* cb = (const char*)(big + (tok0 + (size_t)c * 64) * 6400);
; #pragma unroll
;             for (int i = 0; i < 4; ++i) rk[i] = *(const u32x4*)(cb + offk[i]);
;             if (tid < 256) { rv = *(const u32x4*)(cb + offv); rt = total[(size_t)(b * 64 + c) * 1024 + h * 256 + tid]; }
;         };
.Lgs_596:
	s_cmp_gt_u32 s24, 59
	s_cbranch_scc1 .Lgs_600
	v_lshl_add_u64 v[36:37], v[156:157], 0, s[94:95]
	v_lshl_add_u64 v[40:41], v[154:155], 0, s[94:95]
	v_lshl_add_u64 v[44:45], v[152:153], 0, s[94:95]
	global_load_dwordx4 v[36:39], v[36:37], off
	s_nop 0
	global_load_dwordx4 v[40:43], v[40:41], off
	v_lshl_add_u64 v[48:49], v[150:151], 0, s[94:95]
	global_load_dwordx4 v[44:47], v[44:45], off
	s_nop 0
	global_load_dwordx4 v[48:51], v[48:49], off
	s_and_saveexec_b64 s[36:37], s[8:9]
	s_cbranch_execz .Lgs_599
	v_add3_u32 v52, v195, s24, 4
	v_ashrrev_i32_e32 v53, 31, v52
	v_lshlrev_b64 v[52:53], 12, v[52:53]
	v_lshl_add_u64 v[150:151], v[132:133], 0, v[52:53]
	v_lshl_add_u64 v[52:53], s[12:13], 0, v[142:143]
	v_lshl_add_u64 v[52:53], v[52:53], 0, s[94:95]
	global_load_dwordx4 v[52:55], v[52:53], off
	s_nop 0
	global_load_dword v196, v[150:151], off

; DI void phase_gla_scan(const Params& p, LAS unsigned char* lds) {
;     ...
;         auto step = [&](int c, const bf16x8 (&qc)[8]) {
;             LAS unsigned char* sb = lds + (c & 1) * SET; LAS unsigned char* stb = lds + ST_OFF + (c & 1) * STB;
; #pragma unroll
;             for (int g = 0; g < 4; ++g) { const f32x4 e = *(LAS const f32x4*)(sb + 64 * KR + 64 * VR + (32 * w + 8 * g + 4 * hh) * 4);
;                 st[4 * g] *= e[0]; st[4 * g + 1] *= e[1]; st[4 * g + 2] *= e[2]; st[4 * g + 3] *= e[3]; }
; #pragma unroll
;             for (int sx = 0; sx < 4; ++sx) {
;                 LAS unsigned char* ka = sb + (16 * sx + 8 * hh + tq) * KR + (32 * w + 16 * blk + 4 * tp) * 2;
;                 LAS unsigned char* va = sb + 64 * KR + (16 * sx + 8 * hh + tq) * VR + (16 * blk + 4 * tp) * 2;
;                 const bf16x8 af = cat4(trread(ka), trread(ka + 4 * KR)), bfv = cat4(trread(va), trread(va + 4 * VR));
;                 st = mfma32(af, bfv, st);
;             }
; #pragma unroll
;             for (int g = 0; g < 4; ++g) { u32x2 wv; wv.x = pk2(st[4 * g], st[4 * g + 1]); wv.y = pk2(st[4 * g + 2], st[4 * g + 3]);
;                 *(LAS u32x2*)(stb + l32 * SR + (32 * w + 8 * g + 4 * hh) * 2) = wv; }
;             asm volatile("s_waitcnt lgkmcnt(0)" ::: "memory");
;             __builtin_amdgcn_s_barrier();
;             asm volatile("" ::: "memory");
;             f32x4 acc = {0.f, 0.f, 0.f, 0.f};
; #pragma unroll
;             for (int ks = 0; ks < 8; ++ks) {
;                 const bf16x8 bb = *(LAS const bf16x8*)(stb + (16 * nt + i16) * SR + (32 * ks + 8 * quad) * 2);
;                 acc = __builtin_amdgcn_mfma_f32_16x16x32_bf16(qc[ks], bb, acc, 0, 0, 0);
;             }
; #pragma unroll
;             for (int jj = 0; jj < 4; ++jj) ob[(tok0 + c * 64 + 16 * mt + quad * 4 + jj) * DM + h * 512 + vs * 32 + 16 * nt + i16] = f2bf(acc[jj] * (1.f / 16.f));
;         };
;         __syncthreads();
;         gload(0, rkA, rvA, rtA); lstore(0, rkA, rvA, rtA);
;         gload(1, rkA, rvA, rtA); gload(2, rkB, rvB, rtB); qload(0, qa); qload(1, qn);
;         __syncthreads();
;         for (int c = 0; c < 64; c += 2) {
;             lstore((c + 1) & 1, rkA, rvA, rtA);
;             if (c + 3 < 64) gload(c + 3, rkA, rvA, rtA);
;             step(c, qa);
;             if (c + 2 < 64) qload(c + 2, qa);
;             if (c + 2 < 64) lstore(c & 1, rkB, rvB, rtB);
.Lgs_600:
	ds_read_b128 v[150:153], v176 offset:96
	ds_read_b128 v[154:157], v176 offset:64
	ds_read_b128 v[198:201], v176 offset:32
	ds_read_b128 v[202:205], v176
	s_waitcnt lgkmcnt(3)
	v_pk_mul_f32 v[12:13], v[12:13], v[150:151]
	v_pk_mul_f32 v[14:15], v[14:15], v[152:153]
	ds_read_b64_tr_b16 v[150:151], v190 offset:41984
	ds_read_b64_tr_b16 v[152:153], v190 offset:44288
	s_waitcnt lgkmcnt(4)
	v_pk_mul_f32 v[8:9], v[8:9], v[154:155]
	s_waitcnt lgkmcnt(3)
	v_pk_mul_f32 v[4:5], v[4:5], v[198:199]
	v_pk_mul_f32 v[10:11], v[10:11], v[156:157]
	v_pk_mul_f32 v[6:7], v[6:7], v[200:201]
	s_waitcnt lgkmcnt(2)
	v_pk_mul_f32 v[2:3], v[2:3], v[204:205]
	v_pk_mul_f32 v[0:1], v[0:1], v[202:203]
	ds_read_b64_tr_b16 v[154:155], v177
	ds_read_b64_tr_b16 v[156:157], v177 offset:256
	ds_read_b64_tr_b16 v[198:199], v191 offset:41984
	ds_read_b64_tr_b16 v[200:201], v191 offset:44288
	ds_read_b64_tr_b16 v[202:203], v179
	ds_read_b64_tr_b16 v[204:205], v179 offset:256
	s_waitcnt lgkmcnt(4)
	v_mfma_f32_32x32x16_bf16 v[0:15], v[150:153], v[154:157], v[0:15]
	s_waitcnt lgkmcnt(0)
	v_mfma_f32_32x32x16_bf16 v[0:15], v[198:201], v[202:205], v[0:15]
	ds_read_b64_tr_b16 v[150:151], v192 offset:41984
	ds_read_b64_tr_b16 v[152:153], v192 offset:44288
	ds_read_b64_tr_b16 v[154:155], v180
	ds_read_b64_tr_b16 v[156:157], v180 offset:256
	ds_read_b64_tr_b16 v[198:199], v193 offset:41984
	ds_read_b64_tr_b16 v[200:201], v193 offset:44288
	ds_read_b64_tr_b16 v[202:203], v182
	ds_read_b64_tr_b16 v[204:205], v182 offset:256
	s_waitcnt lgkmcnt(4)
	v_mfma_f32_32x32x16_bf16 v[0:15], v[150:153], v[154:157], v[0:15]
	s_waitcnt lgkmcnt(0)
	v_mfma_f32_32x32x16_bf16 v[0:15], v[198:201], v[202:205], v[0:15]
	v_lshl_add_u64 v[202:203], s[12:13], 0, v[146:147]
	v_add_co_u32_e32 v204, vcc, s46, v202
	s_nop 1
	v_addc_co_u32_e32 v205, vcc, 0, v203, vcc
	v_add_co_u32_e32 v206, vcc, 0x7f42000, v202
	s_nop 5
	v_cvt_pk_bf16_f32 v150, v0, v1
	v_cvt_pk_bf16_f32 v151, v2, v3
	v_cvt_pk_bf16_f32 v152, v4, v5
	v_cvt_pk_bf16_f32 v153, v6, v7
	v_cvt_pk_bf16_f32 v154, v8, v9
	v_cvt_pk_bf16_f32 v155, v10, v11
	v_cvt_pk_bf16_f32 v156, v12, v13
	v_cvt_pk_bf16_f32 v157, v14, v15
	ds_write2_b64 v183, v[150:151], v[152:153] offset1:2
	ds_write2_b64 v183, v[154:155], v[156:157] offset0:4 offset1:6
	s_waitcnt lgkmcnt(0)
	s_barrier
	ds_read_b128 v[150:153], v184
	ds_read_b128 v[154:157], v184 offset:64
	s_waitcnt vmcnt(27) lgkmcnt(1)
	v_mfma_f32_16x16x32_bf16 v[150:153], v[76:79], v[150:153], 0
	v_addc_co_u32_e32 v207, vcc, 0, v203, vcc
	s_waitcnt vmcnt(26) lgkmcnt(0)
	v_mfma_f32_16x16x32_bf16 v[150:153], v[84:87], v[154:157], v[150:153]
	ds_read_b128 v[154:157], v184 offset:128
	ds_read_b128 v[198:201], v184 offset:192
	s_waitcnt vmcnt(25) lgkmcnt(1)
	v_mfma_f32_16x16x32_bf16 v[150:153], v[92:95], v[154:157], v[150:153]
	ds_read_b128 v[154:157], v184 offset:256
	s_waitcnt vmcnt(24) lgkmcnt(1)
	v_mfma_f32_16x16x32_bf16 v[150:153], v[100:103], v[198:201], v[150:153]
	ds_read_b128 v[198:201], v184 offset:320
	s_waitcnt vmcnt(23) lgkmcnt(1)
	v_mfma_f32_16x16x32_bf16 v[150:153], v[104:107], v[154:157], v[150:153]
	ds_read_b128 v[154:157], v184 offset:384
	s_waitcnt vmcnt(22) lgkmcnt(1)
	v_mfma_f32_16x16x32_bf16 v[150:153], v[108:111], v[198:201], v[150:153]
	ds_read_b128 v[198:201], v184 offset:448
	s_waitcnt vmcnt(21) lgkmcnt(1)
	v_mfma_f32_16x16x32_bf16 v[150:153], v[112:115], v[154:157], v[150:153]
	s_waitcnt vmcnt(20) lgkmcnt(0)
	v_mfma_f32_16x16x32_bf16 v[150:153], v[116:119], v[198:201], v[150:153]
	s_nop 7
	v_mul_f32_e32 v130, 0x3d800000, v150
	v_mul_f32_e32 v150, 0x3d800000, v151
	v_mul_f32_e32 v151, 0x3d800000, v152
	v_cvt_pk_bf16_f32 v130, v130, s0
	v_cvt_pk_bf16_f32 v150, v150, s0
	v_cvt_pk_bf16_f32 v151, v151, s0
	global_store_short v[204:205], v130, off offset:-4096
	global_store_short v[204:205], v150, off
	global_store_short v[206:207], v151, off
	v_add_co_u32_e32 v150, vcc, 0x7f43000, v202
	v_mul_f32_e32 v152, 0x3d800000, v153
	s_nop 0
	v_addc_co_u32_e32 v151, vcc, 0, v203, vcc
	v_cvt_pk_bf16_f32 v152, v152, s0
	s_andn2_b64 vcc, exec, s[30:31]
	global_store_short v[150:151], v152, off
	s_cbranch_vccnz .Lgs_585
	v_lshl_add_u64 v[116:117], v[158:159], 0, s[92:93]
	global_load_dwordx4 v[76:79], v[116:117], off
	global_load_dwordx4 v[84:87], v[116:117], off offset:64
	global_load_dwordx4 v[92:95], v[116:117], off offset:128
	global_load_dwordx4 v[100:103], v[116:117], off offset:192
	global_load_dwordx4 v[104:107], v[116:117], off offset:256
	global_load_dwordx4 v[108:111], v[116:117], off offset:320
	global_load_dwordx4 v[112:115], v[116:117], off offset:384
	s_nop 0
	global_load_dwordx4 v[116:119], v[116:117], off offset:448
	s_branch .Lgs_585
.Lgs_585:
	s_add_i32 s24, s24, 2
	v_lshl_add_u64 v[134:135], v[134:135], 0, s[26:27]
	v_lshl_add_u64 v[136:137], v[136:137], 0, s[26:27]
	v_lshl_add_u64 v[138:139], v[138:139], 0, s[26:27]
	v_lshl_add_u64 v[140:141], v[140:141], 0, s[26:27]
	v_lshl_add_u64 v[142:143], v[142:143], 0, s[26:27]
	v_lshl_add_u64 v[144:145], v[144:145], 0, s[26:27]
	v_lshl_add_u64 v[146:147], v[146:147], 0, s[28:29]
	v_lshl_add_u64 v[148:149], v[148:149], 0, s[28:29]
	s_cmp_lt_u32 s24, 60
	s_cbranch_scc1 .Lgs_586
	s_branch .LBB0_586

; __global__ __launch_bounds__(512, 2) void mega(const Params p) {
	.amdhsa_kernel _Z4mega6Params
		.amdhsa_group_segment_fixed_size 0
		.amdhsa_private_segment_fixed_size 0
		.amdhsa_kernarg_size 2624
		.amdhsa_user_sgpr_count 2
		.amdhsa_user_sgpr_dispatch_ptr 0
		.amdhsa_user_sgpr_queue_ptr 0
		.amdhsa_user_sgpr_kernarg_segment_ptr 1
		.amdhsa_user_sgpr_dispatch_id 0
		.amdhsa_user_sgpr_kernarg_preload_length 0
		.amdhsa_user_sgpr_kernarg_preload_offset 0
		.amdhsa_user_sgpr_private_segment_size 0
		.amdhsa_uses_dynamic_stack 0
		.amdhsa_enable_private_segment 0
		.amdhsa_system_sgpr_workgroup_id_x 1
		.amdhsa_system_sgpr_workgroup_id_y 0
		.amdhsa_system_sgpr_workgroup_id_z 0
		.amdhsa_system_sgpr_workgroup_info 0
		.amdhsa_system_vgpr_workitem_id 2
		.amdhsa_next_free_vgpr 256
		.amdhsa_next_free_sgpr 102
		.amdhsa_accum_offset 256
		.amdhsa_reserve_vcc 1
		.amdhsa_float_round_mode_32 0
		.amdhsa_float_round_mode_16_64 0
		.amdhsa_float_denorm_mode_32 3
		.amdhsa_float_denorm_mode_16_64 3
		.amdhsa_dx10_clamp 1
		.amdhsa_ieee_mode 1
		.amdhsa_fp16_overflow 0
		.amdhsa_tg_split 0
		.amdhsa_exception_fp_ieee_invalid_op 0
		.amdhsa_exception_fp_denorm_src 0
		.amdhsa_exception_fp_ieee_div_zero 0
		.amdhsa_exception_fp_ieee_overflow 0
		.amdhsa_exception_fp_ieee_underflow 0
		.amdhsa_exception_fp_ieee_inexact 0
		.amdhsa_exception_int_div_zero 0
	.end_amdhsa_kernel

; __global__ __launch_bounds__(512, 2) void mega(const Params p) {
amdhsa.kernels:
  - .agpr_count:     0
    .args:
      - .offset:         0
        .size:           2368
        .value_kind:     by_value
      - .offset:         2368
        .size:           4
        .value_kind:     hidden_block_count_x
      - .offset:         2372
        .size:           4
        .value_kind:     hidden_block_count_y
      - .offset:         2376
        .size:           4
        .value_kind:     hidden_block_count_z
      - .offset:         2380
        .size:           2
        .value_kind:     hidden_group_size_x
      - .offset:         2382
        .size:           2
        .value_kind:     hidden_group_size_y
      - .offset:         2384
        .size:           2
        .value_kind:     hidden_group_size_z
      - .offset:         2386
        .size:           2
        .value_kind:     hidden_remainder_x
      - .offset:         2388
        .size:           2
        .value_kind:     hidden_remainder_y
      - .offset:         2390
        .size:           2
        .value_kind:     hidden_remainder_z
      - .offset:         2408
        .size:           8
        .value_kind:     hidden_global_offset_x
      - .offset:         2416
        .size:           8
        .value_kind:     hidden_global_offset_y
      - .offset:         2424
        .size:           8
        .value_kind:     hidden_global_offset_z
      - .offset:         2432
        .size:           2
        .value_kind:     hidden_grid_dims
      - .offset:         2456
        .size:           8
        .value_kind:     hidden_multigrid_sync_arg
      - .offset:         2488
        .size:           4
        .value_kind:     hidden_dynamic_lds_size
    .group_segment_fixed_size: 0
    .kernarg_segment_align: 8
    .kernarg_segment_size: 2624
    .language:       OpenCL C
    .language_version:
      - 2
      - 0
    .max_flat_workgroup_size: 512
    .name:           _Z4mega6Params
    .private_segment_fixed_size: 0
    .sgpr_count:     108
    .sgpr_spill_count: 0
    .symbol:         _Z4mega6Params.kd
    .uniform_work_group_size: 1
    .uses_dynamic_stack: false
    .vgpr_count:     256
    .vgpr_spill_count: 0
    .wavefront_size: 64
